# grid barrier: generation-word add removed at the in-loop barrier sites (pollers read the arrival counter)
# speedup vs baseline: 1.0044x; 1.0011x over previous
; __device__ __forceinline__ unsigned xb_ld(unsigned* p)              { return __hip_atomic_load(p, __ATOMIC_RELAXED, __HIP_MEMORY_SCOPE_AGENT); }
; __device__ __forceinline__ unsigned xb_add(unsigned* p, unsigned v) { return __hip_atomic_fetch_add(p, v, __ATOMIC_RELAXED, __HIP_MEMORY_SCOPE_AGENT); }
; #define XB_SPIN(cond, bar) do { unsigned _sp = 0; while (cond) { __builtin_amdgcn_s_sleep(1); \
;     if ((++_sp & 255u) == 0u) { if (xb_ld(&(bar)[XB_TMO])) break; if (_sp > XB_SPIN_CAP) { atomicAdd(&(bar)[XB_TMO], 1u); break; } } } } while (0)
; __device__ __forceinline__ void xcd_barrier(const XcdBarrier& b) {
;     ...
;         if (old + 1u == (gen + 1u) * nloc) {
;             __builtin_amdgcn_fence(__ATOMIC_RELEASE, "agent");
;             asm volatile("s_waitcnt vmcnt(0)" ::: "memory");
;             const unsigned og = xb_add(&bar[XB_TOP], 1u);
;             const unsigned tg = og / nx;
;             if (og + 1u == (tg + 1u) * nx) xb_add(&bar[XB_TOPGEN], 1u);
;             else XB_SPIN(xb_ld(&bar[XB_TOPGEN]) == tg, bar);
;             __builtin_amdgcn_fence(__ATOMIC_ACQUIRE, "agent");
;             xb_add(&bar[XB_XGEN(bx_)], 1u);
.LBB0_539:
	s_or_b64 exec, exec, s[4:5]
	s_and_saveexec_b64 s[4:5], s[6:7]
	s_cbranch_execz .LBB0_541
.LBB0_541:
	s_or_b64 exec, exec, s[4:5]
	s_mov_b64 s[4:5], exec
	v_mbcnt_lo_u32_b32 v2, s4, 0
	v_mbcnt_hi_u32_b32 v2, s5, v2
	v_cmp_eq_u32_e32 vcc, 0, v2
	s_waitcnt vmcnt(0)
	buffer_inv sc1
	s_and_saveexec_b64 s[6:7], vcc
	s_cbranch_execz .LBB0_543
	s_bcnt1_i32_b64 s4, s[4:5]
	v_mov_b32_e32 v2, s4
	v_mov_b32_e32 v4, 0x2000

; __device__ __forceinline__ unsigned xb_ld(unsigned* p)              { return __hip_atomic_load(p, __ATOMIC_RELAXED, __HIP_MEMORY_SCOPE_AGENT); }
; __device__ __forceinline__ unsigned xb_add(unsigned* p, unsigned v) { return __hip_atomic_fetch_add(p, v, __ATOMIC_RELAXED, __HIP_MEMORY_SCOPE_AGENT); }
; #define XB_SPIN(cond, bar) do { unsigned _sp = 0; while (cond) { __builtin_amdgcn_s_sleep(1); \
;     if ((++_sp & 255u) == 0u) { if (xb_ld(&(bar)[XB_TMO])) break; if (_sp > XB_SPIN_CAP) { atomicAdd(&(bar)[XB_TMO], 1u); break; } } } } while (0)
; __device__ __forceinline__ void xcd_barrier(const XcdBarrier& b) {
;     ...
;         if (old + 1u == (gen + 1u) * nloc) {
;             __builtin_amdgcn_fence(__ATOMIC_RELEASE, "agent");
;             asm volatile("s_waitcnt vmcnt(0)" ::: "memory");
;             const unsigned og = xb_add(&bar[XB_TOP], 1u);
;             const unsigned tg = og / nx;
;             if (og + 1u == (tg + 1u) * nx) xb_add(&bar[XB_TOPGEN], 1u);
;             else XB_SPIN(xb_ld(&bar[XB_TOPGEN]) == tg, bar);
;             __builtin_amdgcn_fence(__ATOMIC_ACQUIRE, "agent");
;             xb_add(&bar[XB_XGEN(bx_)], 1u);
.LBB0_747:
	s_or_b64 exec, exec, s[4:5]
	s_and_saveexec_b64 s[4:5], s[6:7]
	s_cbranch_execz .LBB0_749
.LBB0_749:
	s_or_b64 exec, exec, s[4:5]
	s_mov_b64 s[4:5], exec
	v_mbcnt_lo_u32_b32 v2, s4, 0
	v_mbcnt_hi_u32_b32 v2, s5, v2
	v_cmp_eq_u32_e32 vcc, 0, v2
	s_waitcnt vmcnt(0)
	buffer_inv sc1
	s_and_saveexec_b64 s[6:7], vcc
	s_cbranch_execz .LBB0_547
	s_bcnt1_i32_b64 s4, s[4:5]
	v_mov_b32_e32 v2, s4
	v_mov_b32_e32 v4, 0x2000
	s_branch .LBB0_547

; __device__ __forceinline__ unsigned xb_ld(unsigned* p)              { return __hip_atomic_load(p, __ATOMIC_RELAXED, __HIP_MEMORY_SCOPE_AGENT); }
; __device__ __forceinline__ unsigned xb_add(unsigned* p, unsigned v) { return __hip_atomic_fetch_add(p, v, __ATOMIC_RELAXED, __HIP_MEMORY_SCOPE_AGENT); }
; #define XB_SPIN(cond, bar) do { unsigned _sp = 0; while (cond) { __builtin_amdgcn_s_sleep(1); \
;     if ((++_sp & 255u) == 0u) { if (xb_ld(&(bar)[XB_TMO])) break; if (_sp > XB_SPIN_CAP) { atomicAdd(&(bar)[XB_TMO], 1u); break; } } } } while (0)
; __device__ __forceinline__ void xcd_barrier(const XcdBarrier& b) {
;     ...
;         if (old + 1u == (gen + 1u) * nloc) {
;             __builtin_amdgcn_fence(__ATOMIC_RELEASE, "agent");
;             asm volatile("s_waitcnt vmcnt(0)" ::: "memory");
;             const unsigned og = xb_add(&bar[XB_TOP], 1u);
;             const unsigned tg = og / nx;
;             if (og + 1u == (tg + 1u) * nx) xb_add(&bar[XB_TOPGEN], 1u);
;             else XB_SPIN(xb_ld(&bar[XB_TOPGEN]) == tg, bar);
;             __builtin_amdgcn_fence(__ATOMIC_ACQUIRE, "agent");
;             xb_add(&bar[XB_XGEN(bx_)], 1u);
.LBB0_799:
	s_or_b64 exec, exec, s[4:5]
	s_and_saveexec_b64 s[4:5], s[6:7]
	s_cbranch_execz .LBB0_801
.LBB0_801:
	s_or_b64 exec, exec, s[4:5]
	s_mov_b64 s[4:5], exec
	v_mbcnt_lo_u32_b32 v2, s4, 0
	v_mbcnt_hi_u32_b32 v2, s5, v2
	v_cmp_eq_u32_e32 vcc, 0, v2
	s_waitcnt vmcnt(0)
	buffer_inv sc1
	s_and_saveexec_b64 s[6:7], vcc
	s_cbranch_execz .LBB0_803
	s_bcnt1_i32_b64 s4, s[4:5]
	v_mov_b32_e32 v2, s4
	v_mov_b32_e32 v4, 0x2000

; __device__ __forceinline__ unsigned xb_ld(unsigned* p)              { return __hip_atomic_load(p, __ATOMIC_RELAXED, __HIP_MEMORY_SCOPE_AGENT); }
; __device__ __forceinline__ unsigned xb_add(unsigned* p, unsigned v) { return __hip_atomic_fetch_add(p, v, __ATOMIC_RELAXED, __HIP_MEMORY_SCOPE_AGENT); }
; #define XB_SPIN(cond, bar) do { unsigned _sp = 0; while (cond) { __builtin_amdgcn_s_sleep(1); \
;     if ((++_sp & 255u) == 0u) { if (xb_ld(&(bar)[XB_TMO])) break; if (_sp > XB_SPIN_CAP) { atomicAdd(&(bar)[XB_TMO], 1u); break; } } } } while (0)
; __device__ __forceinline__ void xcd_barrier(const XcdBarrier& b) {
;     ...
;         if (old + 1u == (gen + 1u) * nloc) {
;             __builtin_amdgcn_fence(__ATOMIC_RELEASE, "agent");
;             asm volatile("s_waitcnt vmcnt(0)" ::: "memory");
;             const unsigned og = xb_add(&bar[XB_TOP], 1u);
;             const unsigned tg = og / nx;
;             if (og + 1u == (tg + 1u) * nx) xb_add(&bar[XB_TOPGEN], 1u);
;             else XB_SPIN(xb_ld(&bar[XB_TOPGEN]) == tg, bar);
;             __builtin_amdgcn_fence(__ATOMIC_ACQUIRE, "agent");
;             xb_add(&bar[XB_XGEN(bx_)], 1u);
.LBB0_1233:
	s_or_b64 exec, exec, s[4:5]
	s_and_saveexec_b64 s[4:5], s[6:7]
	s_cbranch_execz .LBB0_1235
.LBB0_1235:
	s_or_b64 exec, exec, s[4:5]
	s_mov_b64 s[4:5], exec
	v_mbcnt_lo_u32_b32 v2, s4, 0
	v_mbcnt_hi_u32_b32 v2, s5, v2
	v_cmp_eq_u32_e32 vcc, 0, v2
	s_waitcnt vmcnt(0)
	buffer_inv sc1
	s_and_saveexec_b64 s[6:7], vcc
	s_cbranch_execz .LBB0_1237
	s_bcnt1_i32_b64 s4, s[4:5]
	v_mov_b32_e32 v2, s4
	v_mov_b32_e32 v4, 0x2000

; __device__ __forceinline__ unsigned xb_ld(unsigned* p)              { return __hip_atomic_load(p, __ATOMIC_RELAXED, __HIP_MEMORY_SCOPE_AGENT); }
; __device__ __forceinline__ unsigned xb_add(unsigned* p, unsigned v) { return __hip_atomic_fetch_add(p, v, __ATOMIC_RELAXED, __HIP_MEMORY_SCOPE_AGENT); }
; #define XB_SPIN(cond, bar) do { unsigned _sp = 0; while (cond) { __builtin_amdgcn_s_sleep(1); \
;     if ((++_sp & 255u) == 0u) { if (xb_ld(&(bar)[XB_TMO])) break; if (_sp > XB_SPIN_CAP) { atomicAdd(&(bar)[XB_TMO], 1u); break; } } } } while (0)
; __device__ __forceinline__ void xcd_barrier(const XcdBarrier& b) {
;     ...
;         if (old + 1u == (gen + 1u) * nloc) {
;             __builtin_amdgcn_fence(__ATOMIC_RELEASE, "agent");
;             asm volatile("s_waitcnt vmcnt(0)" ::: "memory");
;             const unsigned og = xb_add(&bar[XB_TOP], 1u);
;             const unsigned tg = og / nx;
;             if (og + 1u == (tg + 1u) * nx) xb_add(&bar[XB_TOPGEN], 1u);
;             else XB_SPIN(xb_ld(&bar[XB_TOPGEN]) == tg, bar);
;             __builtin_amdgcn_fence(__ATOMIC_ACQUIRE, "agent");
;             xb_add(&bar[XB_XGEN(bx_)], 1u);
.LBB0_1292:
	s_or_b64 exec, exec, s[4:5]
	s_and_saveexec_b64 s[4:5], s[6:7]
	s_cbranch_execz .LBB0_1294
.LBB0_1294:
	s_or_b64 exec, exec, s[4:5]
	s_mov_b64 s[4:5], exec
	v_mbcnt_lo_u32_b32 v2, s4, 0
	v_mbcnt_hi_u32_b32 v2, s5, v2
	v_cmp_eq_u32_e32 vcc, 0, v2
	s_waitcnt vmcnt(0)
	buffer_inv sc1
	s_and_saveexec_b64 s[6:7], vcc
	s_cbranch_execz .LBB0_1296
	s_bcnt1_i32_b64 s4, s[4:5]
	v_mov_b32_e32 v2, s4
	v_mov_b32_e32 v4, 0x2000

; __device__ __forceinline__ unsigned xb_ld(unsigned* p)              { return __hip_atomic_load(p, __ATOMIC_RELAXED, __HIP_MEMORY_SCOPE_AGENT); }
; __device__ __forceinline__ unsigned xb_add(unsigned* p, unsigned v) { return __hip_atomic_fetch_add(p, v, __ATOMIC_RELAXED, __HIP_MEMORY_SCOPE_AGENT); }
; #define XB_SPIN(cond, bar) do { unsigned _sp = 0; while (cond) { __builtin_amdgcn_s_sleep(1); \
;     if ((++_sp & 255u) == 0u) { if (xb_ld(&(bar)[XB_TMO])) break; if (_sp > XB_SPIN_CAP) { atomicAdd(&(bar)[XB_TMO], 1u); break; } } } } while (0)
; __device__ __forceinline__ void xcd_barrier(const XcdBarrier& b) {
;     ...
;         if (old + 1u == (gen + 1u) * nloc) {
;             __builtin_amdgcn_fence(__ATOMIC_RELEASE, "agent");
;             asm volatile("s_waitcnt vmcnt(0)" ::: "memory");
;             const unsigned og = xb_add(&bar[XB_TOP], 1u);
;             const unsigned tg = og / nx;
;             if (og + 1u == (tg + 1u) * nx) xb_add(&bar[XB_TOPGEN], 1u);
;             else XB_SPIN(xb_ld(&bar[XB_TOPGEN]) == tg, bar);
;             __builtin_amdgcn_fence(__ATOMIC_ACQUIRE, "agent");
;             xb_add(&bar[XB_XGEN(bx_)], 1u);
.LBB0_1498:
	s_or_b64 exec, exec, s[4:5]
	s_and_saveexec_b64 s[4:5], s[6:7]
	s_cbranch_execz .LBB0_1500
.LBB0_1500:
	s_or_b64 exec, exec, s[4:5]
	s_mov_b64 s[4:5], exec
	v_mbcnt_lo_u32_b32 v2, s4, 0
	v_mbcnt_hi_u32_b32 v2, s5, v2
	v_cmp_eq_u32_e32 vcc, 0, v2
	s_waitcnt vmcnt(0)
	buffer_inv sc1
	s_and_saveexec_b64 s[6:7], vcc
	s_cbranch_execz .LBB0_1502
	s_bcnt1_i32_b64 s4, s[4:5]
	v_mov_b32_e32 v2, s4
	v_mov_b32_e32 v4, 0x2000

; __device__ __forceinline__ unsigned xb_ld(unsigned* p)              { return __hip_atomic_load(p, __ATOMIC_RELAXED, __HIP_MEMORY_SCOPE_AGENT); }
; __device__ __forceinline__ unsigned xb_add(unsigned* p, unsigned v) { return __hip_atomic_fetch_add(p, v, __ATOMIC_RELAXED, __HIP_MEMORY_SCOPE_AGENT); }
; #define XB_SPIN(cond, bar) do { unsigned _sp = 0; while (cond) { __builtin_amdgcn_s_sleep(1); \
;     if ((++_sp & 255u) == 0u) { if (xb_ld(&(bar)[XB_TMO])) break; if (_sp > XB_SPIN_CAP) { atomicAdd(&(bar)[XB_TMO], 1u); break; } } } } while (0)
; __device__ __forceinline__ void xcd_barrier(const XcdBarrier& b) {
;     ...
;         if (old + 1u == (gen + 1u) * nloc) {
;             __builtin_amdgcn_fence(__ATOMIC_RELEASE, "agent");
;             asm volatile("s_waitcnt vmcnt(0)" ::: "memory");
;             const unsigned og = xb_add(&bar[XB_TOP], 1u);
;             const unsigned tg = og / nx;
;             if (og + 1u == (tg + 1u) * nx) xb_add(&bar[XB_TOPGEN], 1u);
;             else XB_SPIN(xb_ld(&bar[XB_TOPGEN]) == tg, bar);
;             __builtin_amdgcn_fence(__ATOMIC_ACQUIRE, "agent");
;             xb_add(&bar[XB_XGEN(bx_)], 1u);
.LBB0_1810:
	s_or_b64 exec, exec, s[4:5]
	s_and_saveexec_b64 s[4:5], s[6:7]
	s_cbranch_execz .LBB0_1812
.LBB0_1812:
	s_or_b64 exec, exec, s[4:5]
	s_mov_b64 s[4:5], exec
	v_mbcnt_lo_u32_b32 v2, s4, 0
	v_mbcnt_hi_u32_b32 v2, s5, v2
	v_cmp_eq_u32_e32 vcc, 0, v2
	s_waitcnt vmcnt(0)
	buffer_inv sc1
	s_and_saveexec_b64 s[6:7], vcc
	s_cbranch_execnz .LBB0_1813
	s_getpc_b64 s[98:99]
